# phase 4: PEER table int8/fp8 conversion folded into the fs_direct K loop (one 32-byte group per thread per K-step), stand-alone conversion loop removed
# speedup vs baseline: 1.0215x; 1.0058x over previous
.LBB0_719:
	s_andn2_b64 vcc, exec, s[6:7]
	s_cbranch_vccnz .LBB0_811
	s_and_b32 s63, s2, 7
	s_ashr_i32 s23, s2, 3
	s_cmp_gt_i32 s23, 7
	s_mov_b64 s[6:7], -1
	s_cbranch_scc0 .LBB0_777
	s_and_b32 s6, s2, -8
	s_sub_i32 s6, s6, 64
	s_or_b32 s65, s6, s63
	s_mul_i32 s7, s65, 13
	s_addk_i32 s7, 0xfc80
	s_cmpk_lt_u32 s6, 0x80
	s_mul_i32 s6, s65, 6
	s_cselect_b32 s8, 6, 13
	s_cselect_b32 s6, s6, s7
	s_add_i32 s7, s6, s8
	s_mul_hi_u32 s9, s6, 0xa3d
	s_mul_i32 s8, s6, 0xa3d
	s_mul_hi_u32 s10, s6, 0x70a3d70a
	s_mul_i32 s11, s6, 0x70a3d70a
	s_mul_hi_u32 s6, s6, 0x3d800000
	s_add_u32 s6, s11, s6
	s_addc_u32 s6, s10, 0
	s_add_u32 s8, s6, s8
	v_mov_b32_e32 v5, 0
	s_addc_u32 s9, 0, s9
	s_mul_hi_u32 s6, s7, 0xa3d
	s_mul_i32 s10, s7, 0xa3d
	s_mul_hi_u32 s11, s7, 0x70a3d70a
	s_mul_i32 s12, s7, 0x70a3d70a
	s_mul_hi_u32 s7, s7, 0x3d800000
	v_mov_b32_e32 v1, v5
	s_add_u32 s7, s12, s7
	s_addc_u32 s7, s11, 0
	v_lshl_add_u64 v[2:3], s[8:9], 0, v[0:1]
	s_mov_b64 s[56:57], 0x600
	s_add_u32 s50, s7, s10
	v_lshl_add_u64 v[6:7], v[2:3], 0, s[56:57]
	s_addc_u32 s51, 0, s6
	s_lshl_b64 s[52:53], s[8:9], 3
	s_lshl_b64 s[54:55], s[8:9], 14
	v_lshrrev_b64 v[82:83], 11, v[6:7]
	v_lshrrev_b64 v[84:85], 3, v[6:7]
	v_lshlrev_b64 v[6:7], 5, v[2:3]
	s_mov_b64 s[8:9], 0xc010
	s_mov_b64 s[58:59], 0x400
	v_lshl_add_u64 v[86:87], v[6:7], 0, s[8:9]
	v_lshl_add_u64 v[6:7], v[2:3], 0, s[58:59]
	s_mov_b64 s[60:61], 0x200
	v_lshrrev_b64 v[88:89], 11, v[6:7]
	v_lshrrev_b64 v[90:91], 3, v[6:7]
	v_lshl_add_u64 v[6:7], v[2:3], 0, s[60:61]
	v_mov_b32_e32 v14, v5
	v_mov_b32_e32 v15, v5
	v_lshrrev_b64 v[92:93], 11, v[6:7]
	v_lshrrev_b64 v[94:95], 3, v[6:7]
	v_mov_b32_e32 v4, v5
	v_mov_b32_e32 v6, v5
	v_mov_b32_e32 v7, v5
	v_mov_b32_e32 v8, v5
	v_mov_b32_e32 v9, v5
	v_mov_b32_e32 v10, v5
	v_mov_b32_e32 v11, v5
	v_mov_b32_e32 v12, v5
	v_mov_b32_e32 v13, v5
	v_mov_b32_e32 v1, 0x42fe0000
	v_mov_b64_e32 v[38:39], v[14:15]
	v_cmp_gt_u64_e64 s[6:7], s[50:51], v[2:3]
	s_waitcnt vmcnt(0)
	v_and_b32_e32 v72, 15, v2
	v_lshlrev_b32_e32 v74, 3, v0
	v_lshrrev_b64 v[76:77], 11, v[2:3]
	v_lshrrev_b64 v[78:79], 3, v[2:3]
	v_lshlrev_b32_e32 v80, 14, v0
	v_mov_b32_e32 v81, v5
	s_mov_b64 s[10:11], 0
	s_mov_b64 s[8:9], -1
	s_mov_b32 s62, 0x41800000
	s_mov_b32 s64, 0x42000000
	s_mov_b32 s66, 0x41980000
	s_mov_b32 s67, 0xc2fe0000
	s_mov_b32 s91, 0x40c0c00
	v_mov_b64_e32 v[36:37], v[12:13]
	v_mov_b64_e32 v[34:35], v[10:11]
	v_mov_b64_e32 v[32:33], v[8:9]
	v_mov_b64_e32 v[30:31], v[6:7]
	v_mov_b64_e32 v[28:29], v[4:5]
	v_mov_b32_e32 v20, v5
	v_mov_b32_e32 v21, v5
	v_mov_b32_e32 v22, v5
	v_mov_b32_e32 v23, v5
	v_mov_b64_e32 v[26:27], v[2:3]
	v_mov_b64_e32 v[24:25], v[0:1]
	s_branch .LBB0_771
.LBB0_771:
	s_cmpk_gt_i32 s65, 0x1ff
	s_waitcnt lgkmcnt(0)
	s_barrier
	s_cbranch_scc1 .LBB0_776
	v_readlane_b32 s6, v254, 2
	s_and_b32 s8, s6, 0xffffff00
	s_ashr_i32 s9, s8, 31
	v_readlane_b32 s7, v254, 3
	s_mov_b32 s10, s6
	v_lshrrev_b32_e32 v1, 2, v0
	s_add_u32 s6, s30, 0x556d9000
	v_and_b32_e32 v2, 3, v0
	s_addc_u32 s7, s31, 0
	v_lshlrev_b32_e32 v164, 12, v1
	v_mov_b32_e32 v165, 0
	v_lshlrev_b32_e32 v162, 4, v2
	v_lshl_add_u64 v[2:3], s[6:7], 0, v[164:165]
	v_mov_b32_e32 v163, v165
	v_lshl_add_u64 v[166:167], v[2:3], 0, v[162:163]
	v_or_b32_e32 v2, 0x80000, v164
	v_mov_b32_e32 v3, v165
	v_lshl_add_u64 v[2:3], s[6:7], 0, v[2:3]
	v_lshl_add_u64 v[2:3], v[2:3], 0, v[162:163]
	s_mov_b64 s[6:7], 0x800
	v_lshl_add_u64 v[168:169], v[2:3], 0, s[6:7]
	s_lshl_b32 s6, s10, 5
	s_and_b32 s64, s6, 0xffffe000
	v_and_b32_e32 v4, 0x1c0, v0
	v_bfe_u32 v5, v0, 2, 4
	s_add_u32 s6, s30, s8
	v_or3_b32 v1, v162, v5, v4
	s_addc_u32 s7, s31, 0
	s_mov_b32 s11, 0
	v_lshlrev_b32_e32 v1, 4, v1
	s_add_u32 s12, s6, 0x557d9000
	v_or_b32_e32 v2, 0x80800, v164
	v_mov_b32_e32 v3, v165
	s_movk_i32 s62, 0x2000
	v_or_b32_e32 v157, 0x2000, v1
	s_addc_u32 s13, s7, 0
	v_lshl_add_u64 v[170:171], s[30:31], 0, v[2:3]
	v_lshl_add_u64 v[172:173], s[30:31], 0, v[164:165]
	s_lshl_b32 s14, s43, 2
	s_mov_b32 s15, s11
	s_mov_b64 s[50:51], 0x1000
	s_movk_i32 s66, 0x1000
	s_mov_b64 s[52:53], 0x1080
	s_mov_b32 s67, 0x556d9000
	s_mov_b64 s[54:55], 0x3000
	s_movk_i32 s68, 0x3000
	s_mov_b64 s[56:57], 0x3080
	s_mov_b64 s[58:59], 0x100
.LBB0_773:
	v_mov_b32_e32 v86, v146
	v_mov_b32_e32 v87, 0
	s_mov_b64 s[6:7], s[0:1]
	s_mov_b64 s[60:61], s[0:1]
	s_load_dwordx2 s[6:7], s[6:7], 0x10
	s_load_dwordx2 s[60:61], s[60:61], 0x30
	s_ashr_i32 s69, s65, 4
	s_lshl_b32 s72, s69, 6
	v_and_b32_e32 v159, 15, v86
	s_lshl_b32 s10, s65, 5
	s_ashr_i32 s73, s72, 31
	s_and_b32 s70, s10, 0x1e0
	s_lshl_b64 s[72:73], s[72:73], 2
	v_or_b32_e32 v2, s10, v159
	s_waitcnt lgkmcnt(0)
	s_add_u32 s60, s60, s72
	v_lshrrev_b32_e32 v2, 1, v2
	s_addc_u32 s61, s61, s73
	v_and_b32_e32 v3, 0xf4, v2
	global_load_dword v2, v3, s[60:61]
	global_load_dword v4, v3, s[60:61] offset:8
	global_load_dwordx4 v[74:77], v[166:167], off
	global_load_dwordx4 v[78:81], v[168:169], off
	v_lshlrev_b32_e32 v3, 16, v86
	v_and_b32_e32 v164, 0x70000, v3
	v_ashrrev_i32_e32 v191, 4, v86
	v_lshl_add_u64 v[8:9], s[6:7], 0, v[164:165]
	v_lshlrev_b32_e32 v6, 3, v191
	v_lshl_add_u64 v[8:9], s[8:9], 2, v[8:9]
	v_ashrrev_i32_e32 v7, 31, v6
	v_lshl_add_u64 v[8:9], v[8:9], 0, s[14:15]
	v_lshlrev_b64 v[6:7], 2, v[6:7]
	global_load_dwordx4 v[66:69], v[166:167], off offset:64
	global_load_dwordx4 v[70:73], v[168:169], off offset:64
	v_add_u32_e32 v164, v87, v1
	v_add_u32_e32 v192, v87, v157
	s_movk_i32 s71, 0xa0
	s_movk_i32 s72, 0x800
	v_mov_b64_e32 v[178:179], v[172:173]
	v_mov_b64_e32 v[180:181], v[170:171]
	s_mov_b32 s73, s11
	v_mov_b32_e32 v122, 0
	v_mov_b32_e32 v123, v165
	v_mov_b32_e32 v124, v165
	v_mov_b32_e32 v125, v165
	v_mov_b32_e32 v90, 0
	v_mov_b32_e32 v91, v165
	v_mov_b32_e32 v92, v165
	v_mov_b32_e32 v93, v165
	v_mov_b32_e32 v94, 0
	v_mov_b32_e32 v95, v165
	v_mov_b32_e32 v96, v165
	v_mov_b32_e32 v97, v165
	v_mov_b32_e32 v110, 0
	v_mov_b32_e32 v111, v165
	v_mov_b32_e32 v112, v165
	v_mov_b32_e32 v113, v165
	v_mov_b32_e32 v118, 0
	v_mov_b32_e32 v119, v165
	v_mov_b32_e32 v120, v165
	v_mov_b32_e32 v121, v165
	v_mov_b32_e32 v126, 0
	v_mov_b32_e32 v127, v165
	v_mov_b32_e32 v128, v165
	v_mov_b32_e32 v129, v165
	v_mov_b32_e32 v130, 0
	v_mov_b32_e32 v131, v165
	v_mov_b32_e32 v132, v165
	v_mov_b32_e32 v133, v165
	v_mov_b32_e32 v114, 0
	v_mov_b32_e32 v115, v165
	v_mov_b32_e32 v116, v165
	v_mov_b32_e32 v117, v165
	v_mov_b32_e32 v106, 0
	v_mov_b32_e32 v107, v165
	v_mov_b32_e32 v108, v165
	v_mov_b32_e32 v109, v165
	v_mov_b32_e32 v102, 0
	v_mov_b32_e32 v103, v165
	v_mov_b32_e32 v104, v165
	v_mov_b32_e32 v105, v165
	v_mov_b32_e32 v88, v165
	v_mov_b32_e32 v89, v165
	v_mov_b32_e32 v98, 0
	v_mov_b32_e32 v99, v165
	v_mov_b32_e32 v100, v165
	v_mov_b32_e32 v101, v165
	v_mov_b32_e32 v134, 0
	v_mov_b32_e32 v135, v165
	v_mov_b32_e32 v136, v165
	v_mov_b32_e32 v137, v165
	s_waitcnt vmcnt(5)
	v_ashrrev_i32_e32 v3, 31, v2
	v_lshlrev_b64 v[2:3], 19, v[2:3]
	s_waitcnt vmcnt(4)
	v_ashrrev_i32_e32 v5, 31, v4
	v_lshl_add_u64 v[2:3], v[8:9], 0, v[2:3]
	v_lshlrev_b64 v[4:5], 19, v[4:5]
	v_lshl_add_u64 v[174:175], v[2:3], 0, v[6:7]
	v_lshl_add_u64 v[4:5], v[8:9], 0, v[4:5]
	v_add_co_u32_e32 v36, vcc, s66, v174
	v_lshl_add_u64 v[176:177], v[4:5], 0, v[6:7]
	s_nop 0
	v_addc_co_u32_e32 v37, vcc, 0, v175, vcc
	v_lshl_add_u64 v[34:35], v[174:175], 0, s[50:51]
	v_lshl_add_u64 v[38:39], v[174:175], 0, s[52:53]
	v_lshl_add_u64 v[40:41], v[176:177], 0, s[50:51]
	v_add_co_u32_e32 v82, vcc, s66, v176
	global_load_dwordx4 v[10:13], v[174:175], off offset:16
	global_load_dwordx4 v[14:17], v[174:175], off
	global_load_dwordx4 v[2:5], v[174:175], off offset:144
	global_load_dwordx4 v[6:9], v[174:175], off offset:128
	global_load_dwordx4 v[26:29], v[176:177], off offset:16
	global_load_dwordx4 v[30:33], v[176:177], off
	global_load_dwordx4 v[18:21], v[176:177], off offset:144
	global_load_dwordx4 v[22:25], v[176:177], off offset:128
	v_addc_co_u32_e32 v83, vcc, 0, v177, vcc
	v_lshl_add_u64 v[84:85], v[176:177], 0, s[52:53]
	global_load_dwordx4 v[58:61], v[36:37], off
	global_load_dwordx4 v[62:65], v[34:35], off offset:16
	global_load_dwordx4 v[54:57], v[36:37], off offset:128
	global_load_dwordx4 v[50:53], v[38:39], off offset:16
	global_load_dwordx4 v[46:49], v[82:83], off
	global_load_dwordx4 v[42:45], v[40:41], off offset:16
	s_nop 0
	global_load_dwordx4 v[38:41], v[82:83], off offset:128
	global_load_dwordx4 v[34:37], v[84:85], off offset:16
	s_waitcnt vmcnt(19)
	ds_write_b128 v164, v[74:77]
	v_lshlrev_b32_e32 v74, 4, v86
	v_add_u32_e32 v75, s64, v87
	s_waitcnt vmcnt(18)
	ds_write_b128 v192, v[78:81]
	v_add_u32_e32 v193, v75, v74
	v_mov_b32_e32 v74, 0
	v_mov_b32_e32 v75, v165
	v_mov_b32_e32 v76, v165
	v_mov_b32_e32 v77, v165
	v_mov_b32_e32 v86, 0
	v_mov_b32_e32 v87, v165
	v_mov_b32_e32 v78, 0
	v_mov_b32_e32 v79, v165
	v_mov_b32_e32 v80, v165
	v_mov_b32_e32 v81, v165
	v_mov_b32_e32 v82, 0
	v_mov_b32_e32 v83, v165
	v_mov_b32_e32 v84, v165
	v_mov_b32_e32 v85, v165
	s_lshr_b32 s83, s65, 8
	s_lshl_b32 s84, s83, 3
	s_add_u32 s94, s0, s84
	s_addc_u32 s95, s1, 0
	s_load_dwordx2 s[76:77], s[94:95], 0xd8
	s_load_dwordx2 s[80:81], s[0:1], 0xc0
	s_and_b32 s86, s65, 0xff
	s_lshr_b32 s87, s86, 7
	s_and_b32 s85, s65, 0x7f
	s_cmp_eq_u32 s83, 0
	s_mov_b32 s78, 0x5c11000
	s_cselect_b32 s78, 0x1c11000, s78
	s_lshl_b32 s84, s87, 24
	s_add_i32 s78, s78, s84
	s_lshl_b32 s84, s85, 14
	s_add_i32 s78, s78, s84
	s_add_u32 s78, s30, s78
	s_addc_u32 s79, s31, 0
	s_mov_b32 s82, 0
	v_lshlrev_b32_e32 v250, 5, v0
	v_bfe_u32 v251, v0, 4, 3
	v_lshlrev_b32_e32 v251, 21, v251
	v_lshrrev_b32_e32 v252, 7, v0
	v_lshl_or_b32 v251, v252, 7, v251
	v_and_b32_e32 v252, 15, v0
	v_lshl_or_b32 v251, v252, 3, v251
	v_and_b32_e32 v252, 0x7f, v0
	v_lshlrev_b32_e32 v252, 5, v252
	s_waitcnt lgkmcnt(0)
	s_lshl_b32 s84, s86, 19
	s_add_u32 s76, s76, s84
	s_addc_u32 s77, s77, 0
	s_lshl_b32 s84, s87, 12
	s_add_u32 s80, s80, s84
	s_addc_u32 s81, s81, 0
	s_cmp_eq_u32 s83, 0
	s_nop 4
	s_cbranch_scc0 .Lpc_nogain
	global_load_dwordx4 v[242:245], v252, s[80:81]
	global_load_dwordx4 v[246:249], v252, s[80:81] offset:16
.Lpc_nogain:
	global_load_dwordx4 v[234:237], v250, s[76:77]
	global_load_dwordx4 v[238:241], v250, s[76:77] offset:16
	s_add_u32 s76, s76, 0x4000
	s_addc_u32 s77, s77, 0
	s_waitcnt lgkmcnt(0)
	s_barrier
.LBB0_774:
	s_nop 0
	ds_read_b128 v[194:197], v193
	ds_read_b128 v[198:201], v193 offset:1024
	s_waitcnt vmcnt(14)
	v_cvt_pk_bf16_f32 v14, v14, v15
	v_cvt_pk_bf16_f32 v15, v16, v17
	v_cvt_pk_bf16_f32 v16, v10, v11
	v_cvt_pk_bf16_f32 v17, v12, v13
	s_waitcnt vmcnt(10)
	v_cvt_pk_bf16_f32 v10, v30, v31
	v_cvt_pk_bf16_f32 v11, v32, v33
	v_cvt_pk_bf16_f32 v12, v26, v27
	v_cvt_pk_bf16_f32 v13, v28, v29
	s_waitcnt lgkmcnt(1)
	v_mfma_f32_16x16x32_bf16 v[130:133], v[194:197], v[14:17], v[130:133]
	ds_read_b128 v[26:29], v193 offset:2048
	s_cmp_lt_u32 s73, 14
	s_cselect_b64 s[6:7], -1, 0
	v_mfma_f32_16x16x32_bf16 v[114:117], v[194:197], v[10:13], v[114:117]
	v_cvt_pk_bf16_f32 v196, v2, v3
	v_cvt_pk_bf16_f32 v197, v4, v5
	ds_read_b128 v[2:5], v193 offset:3072
	s_waitcnt lgkmcnt(2)
	v_mfma_f32_16x16x32_bf16 v[126:129], v[198:201], v[14:17], v[126:129]
	v_cvt_pk_bf16_f32 v194, v6, v7
	v_cvt_pk_bf16_f32 v195, v8, v9
	s_and_b64 s[6:7], s[6:7], exec
	v_mfma_f32_16x16x32_bf16 v[106:109], v[198:201], v[10:13], v[106:109]
	s_waitcnt vmcnt(8)
	v_cvt_pk_bf16_f32 v198, v22, v23
	v_cvt_pk_bf16_f32 v199, v24, v25
	v_cvt_pk_bf16_f32 v200, v18, v19
	s_waitcnt lgkmcnt(1)
	v_mfma_f32_16x16x32_bf16 v[118:121], v[26:29], v[14:17], v[118:121]
	v_cvt_pk_bf16_f32 v201, v20, v21
	ds_read_b128 v[6:9], v193 offset:4096
	ds_read_b128 v[18:21], v193 offset:5120
	s_cselect_b32 s60, s71, 0x3e0
	v_mfma_f32_16x16x32_bf16 v[102:105], v[26:29], v[10:13], v[102:105]
	ds_read_b128 v[22:25], v193 offset:6144
	ds_read_b128 v[26:29], v193 offset:7168
	s_waitcnt vmcnt(1)
	ds_write_b128 v164, v[66:69] offset:16384
	s_sub_i32 s61, s71, 32
	s_waitcnt lgkmcnt(5)
	v_mfma_f32_16x16x32_bf16 v[110:113], v[2:5], v[14:17], v[110:113]
	s_cmp_lt_u32 s73, 14
	s_waitcnt vmcnt(0)
	ds_write_b128 v192, v[70:73] offset:16384
	s_cselect_b64 s[6:7], -1, 0
	s_cmp_eq_u32 s83, 0
	s_cbranch_scc0 .Lpc_f8_t
	v_pk_mul_f32 v[234:235], v[242:243], v[234:235]
	v_pk_mul_f32 v[236:237], v[244:245], v[236:237]
	v_pk_mul_f32 v[238:239], v[246:247], v[238:239]
	v_pk_mul_f32 v[240:241], v[248:249], v[240:241]
	v_mul_f32_e32 v234, 0x42000000, v234
	v_mul_f32_e32 v235, 0x42000000, v235
	v_mul_f32_e32 v236, 0x42000000, v236
	v_mul_f32_e32 v237, 0x42000000, v237
	v_mul_f32_e32 v238, 0x42000000, v238
	v_mul_f32_e32 v239, 0x42000000, v239
	v_mul_f32_e32 v240, 0x42000000, v240
	v_mul_f32_e32 v241, 0x42000000, v241
	v_mul_f32_e32 v234, 0x41980000, v234
	v_mul_f32_e32 v235, 0x41980000, v235
	v_mul_f32_e32 v236, 0x41980000, v236
	v_mul_f32_e32 v237, 0x41980000, v237
	v_mul_f32_e32 v238, 0x41980000, v238
	v_mul_f32_e32 v239, 0x41980000, v239
	v_mul_f32_e32 v240, 0x41980000, v240
	v_mul_f32_e32 v241, 0x41980000, v241
	v_max_f32_e32 v234, 0xc2fe0000, v234
	v_max_f32_e32 v235, 0xc2fe0000, v235
	v_max_f32_e32 v236, 0xc2fe0000, v236
	v_max_f32_e32 v237, 0xc2fe0000, v237
	v_max_f32_e32 v238, 0xc2fe0000, v238
	v_max_f32_e32 v239, 0xc2fe0000, v239
	v_max_f32_e32 v240, 0xc2fe0000, v240
	v_max_f32_e32 v241, 0xc2fe0000, v241
	v_min_f32_e32 v234, 0x42fe0000, v234
	v_min_f32_e32 v235, 0x42fe0000, v235
	v_min_f32_e32 v236, 0x42fe0000, v236
	v_min_f32_e32 v237, 0x42fe0000, v237
	v_min_f32_e32 v238, 0x42fe0000, v238
	v_min_f32_e32 v239, 0x42fe0000, v239
	v_min_f32_e32 v240, 0x42fe0000, v240
	v_min_f32_e32 v241, 0x42fe0000, v241
	v_rndne_f32_e32 v234, v234
	v_rndne_f32_e32 v235, v235
	v_rndne_f32_e32 v236, v236
	v_rndne_f32_e32 v237, v237
	v_rndne_f32_e32 v238, v238
	v_rndne_f32_e32 v239, v239
	v_rndne_f32_e32 v240, v240
	v_rndne_f32_e32 v241, v241
	v_cvt_i32_f32_e32 v234, v234
	v_cvt_i32_f32_e32 v235, v235
	v_cvt_i32_f32_e32 v236, v236
	v_cvt_i32_f32_e32 v237, v237
	v_cvt_i32_f32_e32 v238, v238
	v_cvt_i32_f32_e32 v239, v239
	v_cvt_i32_f32_e32 v240, v240
	v_cvt_i32_f32_e32 v241, v241
	v_and_b32_e32 v234, 0xff, v234
	v_and_b32_e32 v235, 0xff, v235
	v_and_b32_e32 v236, 0xff, v236
	v_lshl_or_b32 v252, v235, 8, v234
	v_lshl_or_b32 v252, v236, 16, v252
	v_lshl_or_b32 v252, v237, 24, v252
	v_and_b32_e32 v238, 0xff, v238
	v_and_b32_e32 v239, 0xff, v239
	v_and_b32_e32 v240, 0xff, v240
	v_lshl_or_b32 v253, v239, 8, v238
	v_lshl_or_b32 v253, v240, 16, v253
	v_lshl_or_b32 v253, v241, 24, v253
	s_branch .Lpc_st_t
.Lpc_f8_t:
	v_mul_f32_e32 v234, 0x41800000, v234
	v_mul_f32_e32 v235, 0x41800000, v235
	v_mul_f32_e32 v236, 0x41800000, v236
	v_mul_f32_e32 v237, 0x41800000, v237
	v_mul_f32_e32 v238, 0x41800000, v238
	v_mul_f32_e32 v239, 0x41800000, v239
	v_mul_f32_e32 v240, 0x41800000, v240
	v_mul_f32_e32 v241, 0x41800000, v241
	v_mov_b32_e32 v252, 0
	v_mov_b32_e32 v253, 0
	v_cvt_pk_fp8_f32 v252, v234, v235
	v_cvt_pk_fp8_f32 v253, v238, v239
	v_cvt_pk_fp8_f32 v252, v236, v237 op_sel:[0,0,1]
	v_cvt_pk_fp8_f32 v253, v240, v241 op_sel:[0,0,1]
.Lpc_st_t:
	global_store_dwordx2 v251, v[252:253], s[78:79]
	global_load_dwordx4 v[234:237], v250, s[76:77]
	global_load_dwordx4 v[238:241], v250, s[76:77] offset:16
	s_add_u32 s78, s78, 0x200
	s_addc_u32 s79, s79, 0
	s_add_i32 s82, s82, 1
	s_cmp_lt_u32 s82, 31
	s_cselect_b32 s84, 0x4000, 0
	s_add_u32 s76, s76, s84
	s_addc_u32 s77, s77, 0
	v_mfma_f32_16x16x32_bf16 v[66:69], v[2:5], v[10:13], v[86:89]
	v_lshl_add_u64 v[2:3], v[178:179], 0, v[162:163]
	v_add_co_u32_e32 v214, vcc, s67, v2
	v_lshl_add_u64 v[4:5], v[180:181], 0, v[162:163]
	s_nop 0
	v_addc_co_u32_e32 v215, vcc, 0, v3, vcc
	v_add_co_u32_e32 v216, vcc, s67, v4
	s_waitcnt lgkmcnt(5)
	v_mfma_f32_16x16x32_bf16 v[70:73], v[6:9], v[14:17], v[94:97]
	v_addc_co_u32_e32 v217, vcc, 0, v5, vcc
	s_and_b64 vcc, s[6:7], exec
	s_waitcnt lgkmcnt(4)
	v_mfma_f32_16x16x32_bf16 v[86:89], v[18:21], v[14:17], v[90:93]
	s_cselect_b32 s10, s72, 0x3c00
	s_cselect_b32 s6, s61, 0x3e0
	s_lshl_b64 s[74:75], s[10:11], 2
	v_mfma_f32_16x16x32_bf16 v[90:93], v[18:21], v[10:13], v[98:101]
	global_load_dwordx4 v[94:97], v[214:215], off offset:128
	s_nop 1
	global_load_dwordx4 v[98:101], v[216:217], off offset:128
	s_waitcnt vmcnt(9)
	v_cvt_pk_bf16_f32 v210, v58, v59
	v_cvt_pk_bf16_f32 v211, v60, v61
	v_mfma_f32_16x16x32_bf16 v[78:81], v[6:9], v[10:13], v[78:81]
	v_lshl_add_u64 v[6:7], v[174:175], 0, s[74:75]
	s_waitcnt vmcnt(8)
	v_cvt_pk_bf16_f32 v212, v62, v63
	v_cvt_pk_bf16_f32 v213, v64, v65
	s_waitcnt lgkmcnt(3)
	v_mfma_f32_16x16x32_bf16 v[74:77], v[22:25], v[14:17], v[74:77]
	s_min_u32 s10, s73, 12
	s_mov_b32 s7, s11
	s_lshl_b32 s10, s10, 12
	v_mfma_f32_16x16x32_bf16 v[82:85], v[22:25], v[10:13], v[82:85]
	v_lshl_add_u64 v[22:23], v[176:177], 0, s[74:75]
	s_lshl_b64 s[6:7], s[6:7], 1
	s_mov_b32 s61, s11
	s_waitcnt lgkmcnt(2)
	v_mfma_f32_16x16x32_bf16 v[202:205], v[26:29], v[14:17], v[122:125]
	v_lshl_add_u64 v[180:181], v[180:181], 0, s[58:59]
	v_lshl_add_u64 v[178:179], v[178:179], 0, s[58:59]
	s_add_i32 s73, s73, 2
	v_mfma_f32_16x16x32_bf16 v[134:137], v[26:29], v[10:13], v[134:137]
	global_load_dwordx4 v[10:13], v[6:7], off offset:16
	global_load_dwordx4 v[14:17], v[6:7], off
	global_load_dwordx4 v[2:5], v[6:7], off offset:144
	s_nop 0
	global_load_dwordx4 v[6:9], v[6:7], off offset:128
	s_nop 0
	global_load_dwordx4 v[26:29], v[22:23], off offset:16
	global_load_dwordx4 v[30:33], v[22:23], off
	global_load_dwordx4 v[18:21], v[22:23], off offset:144
	s_nop 0
	global_load_dwordx4 v[22:25], v[22:23], off offset:128
	s_waitcnt lgkmcnt(0)
	s_barrier
	s_waitcnt vmcnt(10)
	s_cmp_eq_u32 s83, 0
	s_cbranch_scc0 .Lpc_f8_a
	v_pk_mul_f32 v[234:235], v[242:243], v[234:235]
	v_pk_mul_f32 v[236:237], v[244:245], v[236:237]
	v_pk_mul_f32 v[238:239], v[246:247], v[238:239]
	v_pk_mul_f32 v[240:241], v[248:249], v[240:241]
	v_mul_f32_e32 v234, 0x42000000, v234
	v_mul_f32_e32 v235, 0x42000000, v235
	v_mul_f32_e32 v236, 0x42000000, v236
	v_mul_f32_e32 v237, 0x42000000, v237
	v_mul_f32_e32 v238, 0x42000000, v238
	v_mul_f32_e32 v239, 0x42000000, v239
	v_mul_f32_e32 v240, 0x42000000, v240
	v_mul_f32_e32 v241, 0x42000000, v241
	v_mul_f32_e32 v234, 0x41980000, v234
	v_mul_f32_e32 v235, 0x41980000, v235
	v_mul_f32_e32 v236, 0x41980000, v236
	v_mul_f32_e32 v237, 0x41980000, v237
	v_mul_f32_e32 v238, 0x41980000, v238
	v_mul_f32_e32 v239, 0x41980000, v239
	v_mul_f32_e32 v240, 0x41980000, v240
	v_mul_f32_e32 v241, 0x41980000, v241
	v_max_f32_e32 v234, 0xc2fe0000, v234
	v_max_f32_e32 v235, 0xc2fe0000, v235
	v_max_f32_e32 v236, 0xc2fe0000, v236
	v_max_f32_e32 v237, 0xc2fe0000, v237
	v_max_f32_e32 v238, 0xc2fe0000, v238
	v_max_f32_e32 v239, 0xc2fe0000, v239
	v_max_f32_e32 v240, 0xc2fe0000, v240
	v_max_f32_e32 v241, 0xc2fe0000, v241
	v_min_f32_e32 v234, 0x42fe0000, v234
	v_min_f32_e32 v235, 0x42fe0000, v235
	v_min_f32_e32 v236, 0x42fe0000, v236
	v_min_f32_e32 v237, 0x42fe0000, v237
	v_min_f32_e32 v238, 0x42fe0000, v238
	v_min_f32_e32 v239, 0x42fe0000, v239
	v_min_f32_e32 v240, 0x42fe0000, v240
	v_min_f32_e32 v241, 0x42fe0000, v241
	v_rndne_f32_e32 v234, v234
	v_rndne_f32_e32 v235, v235
	v_rndne_f32_e32 v236, v236
	v_rndne_f32_e32 v237, v237
	v_rndne_f32_e32 v238, v238
	v_rndne_f32_e32 v239, v239
	v_rndne_f32_e32 v240, v240
	v_rndne_f32_e32 v241, v241
	v_cvt_i32_f32_e32 v234, v234
	v_cvt_i32_f32_e32 v235, v235
	v_cvt_i32_f32_e32 v236, v236
	v_cvt_i32_f32_e32 v237, v237
	v_cvt_i32_f32_e32 v238, v238
	v_cvt_i32_f32_e32 v239, v239
	v_cvt_i32_f32_e32 v240, v240
	v_cvt_i32_f32_e32 v241, v241
	v_and_b32_e32 v234, 0xff, v234
	v_and_b32_e32 v235, 0xff, v235
	v_and_b32_e32 v236, 0xff, v236
	v_lshl_or_b32 v252, v235, 8, v234
	v_lshl_or_b32 v252, v236, 16, v252
	v_lshl_or_b32 v252, v237, 24, v252
	v_and_b32_e32 v238, 0xff, v238
	v_and_b32_e32 v239, 0xff, v239
	v_and_b32_e32 v240, 0xff, v240
	v_lshl_or_b32 v253, v239, 8, v238
	v_lshl_or_b32 v253, v240, 16, v253
	v_lshl_or_b32 v253, v241, 24, v253
	s_branch .Lpc_st_a

.Lpc_st_a:
	global_store_dwordx2 v251, v[252:253], s[78:79]
	global_load_dwordx4 v[234:237], v250, s[76:77]
	global_load_dwordx4 v[238:241], v250, s[76:77] offset:16
	s_add_u32 s78, s78, 0x200
	s_addc_u32 s79, s79, 0
	s_add_i32 s82, s82, 1
	s_cmp_lt_u32 s82, 31
	s_cselect_b32 s84, 0x4000, 0
	s_add_u32 s76, s76, s84
	s_addc_u32 s77, s77, 0
	ds_read_b128 v[122:125], v193 offset:16384
	ds_read_b128 v[206:209], v193 offset:17408
	s_waitcnt lgkmcnt(1)
	v_mfma_f32_16x16x32_bf16 v[130:133], v[122:125], v[194:197], v[130:133]
	s_addk_i32 s71, 0x80
	s_addk_i32 s72, 0x800
	v_mfma_f32_16x16x32_bf16 v[114:117], v[122:125], v[198:201], v[114:117]
	s_waitcnt lgkmcnt(0)
	v_mfma_f32_16x16x32_bf16 v[126:129], v[206:209], v[194:197], v[126:129]
	v_mfma_f32_16x16x32_bf16 v[106:109], v[206:209], v[198:201], v[106:109]
	ds_read_b128 v[122:125], v193 offset:18432
	ds_read_b128 v[206:209], v193 offset:19456
	s_waitcnt lgkmcnt(1)
	v_mfma_f32_16x16x32_bf16 v[118:121], v[122:125], v[194:197], v[118:121]
	v_mfma_f32_16x16x32_bf16 v[102:105], v[122:125], v[198:201], v[102:105]
	s_waitcnt lgkmcnt(0)
	v_mfma_f32_16x16x32_bf16 v[110:113], v[206:209], v[194:197], v[110:113]
	v_mfma_f32_16x16x32_bf16 v[66:69], v[206:209], v[198:201], v[66:69]
	ds_read_b128 v[122:125], v193 offset:20480
	ds_read_b128 v[206:209], v193 offset:21504
	ds_read_b128 v[58:61], v193 offset:22528
	ds_read_b128 v[62:65], v193 offset:23552
	s_waitcnt lgkmcnt(3)
	v_mfma_f32_16x16x32_bf16 v[70:73], v[122:125], v[194:197], v[70:73]
	s_waitcnt lgkmcnt(2)
	v_mfma_f32_16x16x32_bf16 v[86:89], v[206:209], v[194:197], v[86:89]
	s_waitcnt lgkmcnt(1)
	v_mfma_f32_16x16x32_bf16 v[74:77], v[58:61], v[194:197], v[74:77]
	s_waitcnt lgkmcnt(0)
	v_mfma_f32_16x16x32_bf16 v[194:197], v[62:65], v[194:197], v[202:205]
	s_nop 2
	global_load_dwordx4 v[202:205], v[214:215], off offset:192
	s_nop 0
	global_load_dwordx4 v[214:217], v[216:217], off offset:192
	s_waitcnt vmcnt(14)
	ds_write_b128 v164, v[94:97]
	s_waitcnt vmcnt(13)
	ds_write_b128 v192, v[98:101]
	v_mfma_f32_16x16x32_bf16 v[78:81], v[122:125], v[198:201], v[78:81]
	s_waitcnt lgkmcnt(0)
	s_barrier
	s_waitcnt vmcnt(2)
	s_cmp_eq_u32 s83, 0
	s_cbranch_scc0 .Lpc_f8_b
	v_pk_mul_f32 v[234:235], v[242:243], v[234:235]
	v_pk_mul_f32 v[236:237], v[244:245], v[236:237]
	v_pk_mul_f32 v[238:239], v[246:247], v[238:239]
	v_pk_mul_f32 v[240:241], v[248:249], v[240:241]
	v_mul_f32_e32 v234, 0x42000000, v234
	v_mul_f32_e32 v235, 0x42000000, v235
	v_mul_f32_e32 v236, 0x42000000, v236
	v_mul_f32_e32 v237, 0x42000000, v237
	v_mul_f32_e32 v238, 0x42000000, v238
	v_mul_f32_e32 v239, 0x42000000, v239
	v_mul_f32_e32 v240, 0x42000000, v240
	v_mul_f32_e32 v241, 0x42000000, v241
	v_mul_f32_e32 v234, 0x41980000, v234
	v_mul_f32_e32 v235, 0x41980000, v235
	v_mul_f32_e32 v236, 0x41980000, v236
	v_mul_f32_e32 v237, 0x41980000, v237
	v_mul_f32_e32 v238, 0x41980000, v238
	v_mul_f32_e32 v239, 0x41980000, v239
	v_mul_f32_e32 v240, 0x41980000, v240
	v_mul_f32_e32 v241, 0x41980000, v241
	v_max_f32_e32 v234, 0xc2fe0000, v234
	v_max_f32_e32 v235, 0xc2fe0000, v235
	v_max_f32_e32 v236, 0xc2fe0000, v236
	v_max_f32_e32 v237, 0xc2fe0000, v237
	v_max_f32_e32 v238, 0xc2fe0000, v238
	v_max_f32_e32 v239, 0xc2fe0000, v239
	v_max_f32_e32 v240, 0xc2fe0000, v240
	v_max_f32_e32 v241, 0xc2fe0000, v241
	v_min_f32_e32 v234, 0x42fe0000, v234
	v_min_f32_e32 v235, 0x42fe0000, v235
	v_min_f32_e32 v236, 0x42fe0000, v236
	v_min_f32_e32 v237, 0x42fe0000, v237
	v_min_f32_e32 v238, 0x42fe0000, v238
	v_min_f32_e32 v239, 0x42fe0000, v239
	v_min_f32_e32 v240, 0x42fe0000, v240
	v_min_f32_e32 v241, 0x42fe0000, v241
	v_rndne_f32_e32 v234, v234
	v_rndne_f32_e32 v235, v235
	v_rndne_f32_e32 v236, v236
	v_rndne_f32_e32 v237, v237
	v_rndne_f32_e32 v238, v238
	v_rndne_f32_e32 v239, v239
	v_rndne_f32_e32 v240, v240
	v_rndne_f32_e32 v241, v241
	v_cvt_i32_f32_e32 v234, v234
	v_cvt_i32_f32_e32 v235, v235
	v_cvt_i32_f32_e32 v236, v236
	v_cvt_i32_f32_e32 v237, v237
	v_cvt_i32_f32_e32 v238, v238
	v_cvt_i32_f32_e32 v239, v239
	v_cvt_i32_f32_e32 v240, v240
	v_cvt_i32_f32_e32 v241, v241
	v_and_b32_e32 v234, 0xff, v234
	v_and_b32_e32 v235, 0xff, v235
	v_and_b32_e32 v236, 0xff, v236
	v_lshl_or_b32 v252, v235, 8, v234
	v_lshl_or_b32 v252, v236, 16, v252
	v_lshl_or_b32 v252, v237, 24, v252
	v_and_b32_e32 v238, 0xff, v238
	v_and_b32_e32 v239, 0xff, v239
	v_and_b32_e32 v240, 0xff, v240
	v_lshl_or_b32 v253, v239, 8, v238
	v_lshl_or_b32 v253, v240, 16, v253
	v_lshl_or_b32 v253, v241, 24, v253
	s_branch .Lpc_st_b

.Lpc_st_b:
	global_store_dwordx2 v251, v[252:253], s[78:79]
	global_load_dwordx4 v[234:237], v250, s[76:77]
	global_load_dwordx4 v[238:241], v250, s[76:77] offset:16
	s_add_u32 s78, s78, 0x200
	s_addc_u32 s79, s79, 0
	s_add_i32 s82, s82, 1
	s_cmp_lt_u32 s82, 31
	s_cselect_b32 s84, 0x4000, 0
	s_add_u32 s76, s76, s84
	s_addc_u32 s77, s77, 0
	v_mfma_f32_16x16x32_bf16 v[90:93], v[206:209], v[198:201], v[90:93]
	v_cvt_pk_bf16_f32 v206, v46, v47
	v_cvt_pk_bf16_f32 v207, v48, v49
	v_cvt_pk_bf16_f32 v208, v42, v43
	v_mfma_f32_16x16x32_bf16 v[82:85], v[58:61], v[198:201], v[82:85]
	v_cvt_pk_bf16_f32 v209, v44, v45
	ds_read_b128 v[42:45], v193
	ds_read_b128 v[46:49], v193 offset:1024
	v_cvt_pk_bf16_f32 v122, v54, v55
	v_mfma_f32_16x16x32_bf16 v[134:137], v[62:65], v[198:201], v[134:137]
	v_cvt_pk_bf16_f32 v198, v38, v39
	v_cvt_pk_bf16_f32 v199, v40, v41
	v_cvt_pk_bf16_f32 v200, v34, v35
	v_cvt_pk_bf16_f32 v201, v36, v37
	ds_read_b128 v[34:37], v193 offset:2048
	ds_read_b128 v[38:41], v193 offset:3072
	s_waitcnt lgkmcnt(3)
	v_mfma_f32_16x16x32_bf16 v[94:97], v[42:45], v[210:213], v[130:133]
	v_cvt_pk_bf16_f32 v123, v56, v57
	v_cvt_pk_bf16_f32 v124, v50, v51
	v_cvt_pk_bf16_f32 v125, v52, v53
	v_mfma_f32_16x16x32_bf16 v[98:101], v[42:45], v[206:209], v[114:117]
	v_lshl_add_u64 v[42:43], v[174:175], 0, s[10:11]
	v_lshl_add_u64 v[130:131], v[166:167], 0, s[6:7]
	v_lshl_add_u64 v[132:133], v[168:169], 0, s[6:7]
	s_waitcnt lgkmcnt(1)
	v_mfma_f32_16x16x32_bf16 v[118:121], v[34:37], v[210:213], v[118:121]
	v_lshl_add_u64 v[44:45], v[176:177], 0, s[10:11]
	v_lshl_add_u64 v[226:227], v[44:45], 0, s[54:55]
	v_mfma_f32_16x16x32_bf16 v[102:105], v[34:37], v[206:209], v[102:105]
	s_waitcnt lgkmcnt(0)
	v_mfma_f32_16x16x32_bf16 v[110:113], v[38:41], v[210:213], v[110:113]
	v_mfma_f32_16x16x32_bf16 v[66:69], v[38:41], v[206:209], v[66:69]
	ds_read_b128 v[34:37], v193 offset:4096
	ds_read_b128 v[38:41], v193 offset:5120
	ds_read_b128 v[114:117], v193 offset:6144
	v_mfma_f32_16x16x32_bf16 v[126:129], v[46:49], v[210:213], v[126:129]
	v_mfma_f32_16x16x32_bf16 v[106:109], v[46:49], v[206:209], v[106:109]
	v_add_co_u32_e64 v48, s[6:7], s68, v42
	v_lshl_add_u64 v[46:47], v[42:43], 0, s[54:55]
	s_nop 0
	v_addc_co_u32_e64 v49, s[6:7], 0, v43, s[6:7]
	v_add_co_u32_e64 v228, s[6:7], s68, v44
	v_lshl_add_u64 v[42:43], v[42:43], 0, s[56:57]
	s_nop 0
	v_addc_co_u32_e64 v229, s[6:7], 0, v45, s[6:7]
	s_waitcnt lgkmcnt(2)
	v_mfma_f32_16x16x32_bf16 v[70:73], v[34:37], v[210:213], v[70:73]
	global_load_dwordx4 v[58:61], v[48:49], off
	global_load_dwordx4 v[62:65], v[46:47], off offset:16
	global_load_dwordx4 v[54:57], v[48:49], off offset:128
	global_load_dwordx4 v[50:53], v[42:43], off offset:16
	s_lshl_b64 s[6:7], s[60:61], 1
	v_mfma_f32_16x16x32_bf16 v[78:81], v[34:37], v[206:209], v[78:81]
	v_lshl_add_u64 v[34:35], v[44:45], 0, s[56:57]
	global_load_dwordx4 v[46:49], v[228:229], off
	global_load_dwordx4 v[42:45], v[226:227], off offset:16
	s_waitcnt lgkmcnt(1)
	v_mfma_f32_16x16x32_bf16 v[218:221], v[38:41], v[210:213], v[86:89]
	s_nop 2
	ds_read_b128 v[86:89], v193 offset:7168
	v_mfma_f32_16x16x32_bf16 v[222:225], v[38:41], v[206:209], v[90:93]
	global_load_dwordx4 v[38:41], v[228:229], off offset:128
	s_nop 0
	global_load_dwordx4 v[34:37], v[34:35], off offset:16
	s_nop 0
	global_load_dwordx4 v[226:229], v[130:131], off
	global_load_dwordx4 v[230:233], v[132:133], off
	s_waitcnt vmcnt(14)
	ds_write_b128 v164, v[202:205] offset:16384
	s_waitcnt vmcnt(13)
	ds_write_b128 v192, v[214:217] offset:16384
	s_waitcnt lgkmcnt(2)
	v_mfma_f32_16x16x32_bf16 v[194:197], v[86:89], v[210:213], v[194:197]
	s_waitcnt lgkmcnt(0)
	s_barrier
	s_waitcnt vmcnt(10)
	s_cmp_eq_u32 s83, 0
	s_cbranch_scc0 .Lpc_f8_c
	v_pk_mul_f32 v[234:235], v[242:243], v[234:235]
	v_pk_mul_f32 v[236:237], v[244:245], v[236:237]
	v_pk_mul_f32 v[238:239], v[246:247], v[238:239]
	v_pk_mul_f32 v[240:241], v[248:249], v[240:241]
	v_mul_f32_e32 v234, 0x42000000, v234
	v_mul_f32_e32 v235, 0x42000000, v235
	v_mul_f32_e32 v236, 0x42000000, v236
	v_mul_f32_e32 v237, 0x42000000, v237
	v_mul_f32_e32 v238, 0x42000000, v238
	v_mul_f32_e32 v239, 0x42000000, v239
	v_mul_f32_e32 v240, 0x42000000, v240
	v_mul_f32_e32 v241, 0x42000000, v241
	v_mul_f32_e32 v234, 0x41980000, v234
	v_mul_f32_e32 v235, 0x41980000, v235
	v_mul_f32_e32 v236, 0x41980000, v236
	v_mul_f32_e32 v237, 0x41980000, v237
	v_mul_f32_e32 v238, 0x41980000, v238
	v_mul_f32_e32 v239, 0x41980000, v239
	v_mul_f32_e32 v240, 0x41980000, v240
	v_mul_f32_e32 v241, 0x41980000, v241
	v_max_f32_e32 v234, 0xc2fe0000, v234
	v_max_f32_e32 v235, 0xc2fe0000, v235
	v_max_f32_e32 v236, 0xc2fe0000, v236
	v_max_f32_e32 v237, 0xc2fe0000, v237
	v_max_f32_e32 v238, 0xc2fe0000, v238
	v_max_f32_e32 v239, 0xc2fe0000, v239
	v_max_f32_e32 v240, 0xc2fe0000, v240
	v_max_f32_e32 v241, 0xc2fe0000, v241
	v_min_f32_e32 v234, 0x42fe0000, v234
	v_min_f32_e32 v235, 0x42fe0000, v235
	v_min_f32_e32 v236, 0x42fe0000, v236
	v_min_f32_e32 v237, 0x42fe0000, v237
	v_min_f32_e32 v238, 0x42fe0000, v238
	v_min_f32_e32 v239, 0x42fe0000, v239
	v_min_f32_e32 v240, 0x42fe0000, v240
	v_min_f32_e32 v241, 0x42fe0000, v241
	v_rndne_f32_e32 v234, v234
	v_rndne_f32_e32 v235, v235
	v_rndne_f32_e32 v236, v236
	v_rndne_f32_e32 v237, v237
	v_rndne_f32_e32 v238, v238
	v_rndne_f32_e32 v239, v239
	v_rndne_f32_e32 v240, v240
	v_rndne_f32_e32 v241, v241
	v_cvt_i32_f32_e32 v234, v234
	v_cvt_i32_f32_e32 v235, v235
	v_cvt_i32_f32_e32 v236, v236
	v_cvt_i32_f32_e32 v237, v237
	v_cvt_i32_f32_e32 v238, v238
	v_cvt_i32_f32_e32 v239, v239
	v_cvt_i32_f32_e32 v240, v240
	v_cvt_i32_f32_e32 v241, v241
	v_and_b32_e32 v234, 0xff, v234
	v_and_b32_e32 v235, 0xff, v235
	v_and_b32_e32 v236, 0xff, v236
	v_lshl_or_b32 v252, v235, 8, v234
	v_lshl_or_b32 v252, v236, 16, v252
	v_lshl_or_b32 v252, v237, 24, v252
	v_and_b32_e32 v238, 0xff, v238
	v_and_b32_e32 v239, 0xff, v239
	v_and_b32_e32 v240, 0xff, v240
	v_lshl_or_b32 v253, v239, 8, v238
	v_lshl_or_b32 v253, v240, 16, v253
	v_lshl_or_b32 v253, v241, 24, v253
	s_branch .Lpc_st_c

.Lpc_st_c:
	global_store_dwordx2 v251, v[252:253], s[78:79]
	global_load_dwordx4 v[234:237], v250, s[76:77]
	global_load_dwordx4 v[238:241], v250, s[76:77] offset:16
	s_add_u32 s78, s78, 0x200
	s_addc_u32 s79, s79, 0
	s_add_i32 s82, s82, 1
	s_cmp_lt_u32 s82, 31
	s_cselect_b32 s84, 0x4000, 0
	s_add_u32 s76, s76, s84
	s_addc_u32 s77, s77, 0
	v_mfma_f32_16x16x32_bf16 v[134:137], v[86:89], v[206:209], v[134:137]
	ds_read_b128 v[86:89], v193 offset:16384
	ds_read_b128 v[90:93], v193 offset:17408
	v_mfma_f32_16x16x32_bf16 v[74:77], v[114:117], v[210:213], v[74:77]
	v_mfma_f32_16x16x32_bf16 v[82:85], v[114:117], v[206:209], v[82:85]
	s_waitcnt lgkmcnt(1)
	v_mfma_f32_16x16x32_bf16 v[130:133], v[86:89], v[122:125], v[94:97]
	v_mfma_f32_16x16x32_bf16 v[114:117], v[86:89], v[198:201], v[98:101]
	s_waitcnt lgkmcnt(0)
	v_mfma_f32_16x16x32_bf16 v[126:129], v[90:93], v[122:125], v[126:129]
	v_mfma_f32_16x16x32_bf16 v[106:109], v[90:93], v[198:201], v[106:109]
	ds_read_b128 v[86:89], v193 offset:18432
	ds_read_b128 v[90:93], v193 offset:19456
	s_waitcnt lgkmcnt(1)
	v_mfma_f32_16x16x32_bf16 v[118:121], v[86:89], v[122:125], v[118:121]
	v_mfma_f32_16x16x32_bf16 v[102:105], v[86:89], v[198:201], v[102:105]
	s_waitcnt lgkmcnt(0)
	v_mfma_f32_16x16x32_bf16 v[86:89], v[90:93], v[198:201], v[66:69]
	s_nop 2
	ds_read_b128 v[66:69], v193 offset:20480
	ds_read_b128 v[98:101], v193 offset:21504
	ds_read_b128 v[202:205], v193 offset:22528
	ds_read_b128 v[206:209], v193 offset:23552
	s_waitcnt lgkmcnt(3)
	v_mfma_f32_16x16x32_bf16 v[94:97], v[66:69], v[122:125], v[70:73]
	s_nop 2
	v_lshl_add_u64 v[70:71], v[168:169], 0, s[6:7]
	v_mfma_f32_16x16x32_bf16 v[78:81], v[66:69], v[198:201], v[78:81]
	v_lshl_add_u64 v[66:67], v[166:167], 0, s[6:7]
	global_load_dwordx4 v[66:69], v[66:67], off
	s_nop 0
	global_load_dwordx4 v[70:73], v[70:71], off
	v_mfma_f32_16x16x32_bf16 v[110:113], v[90:93], v[122:125], v[110:113]
	s_waitcnt vmcnt(6)
	ds_write_b128 v164, v[226:229]
	s_waitcnt vmcnt(5)
	ds_write_b128 v192, v[230:233]
	s_waitcnt lgkmcnt(4)
	v_mfma_f32_16x16x32_bf16 v[90:93], v[98:101], v[122:125], v[218:221]
	s_waitcnt lgkmcnt(0)
	s_barrier
	v_mfma_f32_16x16x32_bf16 v[98:101], v[98:101], v[198:201], v[222:225]
	v_mfma_f32_16x16x32_bf16 v[74:77], v[202:205], v[122:125], v[74:77]
	v_mfma_f32_16x16x32_bf16 v[82:85], v[202:205], v[198:201], v[82:85]
	v_mfma_f32_16x16x32_bf16 v[122:125], v[206:209], v[122:125], v[194:197]
	v_mfma_f32_16x16x32_bf16 v[134:137], v[206:209], v[198:201], v[134:137]
	s_cbranch_vccnz .LBB0_774
	s_lshl_b32 s6, s69, 2
	s_or_b32 s6, s6, s89
	s_ashr_i32 s7, s6, 31
	s_lshl_b64 s[6:7], s[6:7], 9
	s_or_b32 s6, s6, s70
	v_or_b32_e32 v2, s6, v159
	v_mov_b32_e32 v3, s7
	v_lshlrev_b64 v[2:3], 9, v[2:3]
	v_lshlrev_b32_e32 v4, 2, v191
	v_lshl_add_u64 v[2:3], s[12:13], 0, v[2:3]
	v_ashrrev_i32_e32 v5, 31, v4
	v_lshl_add_u64 v[2:3], v[4:5], 1, v[2:3]
	v_cvt_pk_bf16_f32 v4, v130, v131
	v_cvt_pk_bf16_f32 v5, v132, v133
	global_store_dwordx2 v[2:3], v[4:5], off
	v_cvt_pk_bf16_f32 v4, v126, v127
	v_cvt_pk_bf16_f32 v5, v128, v129
	global_store_dwordx2 v[2:3], v[4:5], off offset:32
	v_cvt_pk_bf16_f32 v4, v118, v119
	v_cvt_pk_bf16_f32 v5, v120, v121
	global_store_dwordx2 v[2:3], v[4:5], off offset:64
	v_cvt_pk_bf16_f32 v4, v110, v111
	v_cvt_pk_bf16_f32 v5, v112, v113
	global_store_dwordx2 v[2:3], v[4:5], off offset:96
	v_cvt_pk_bf16_f32 v4, v94, v95
	v_cvt_pk_bf16_f32 v5, v96, v97
	global_store_dwordx2 v[2:3], v[4:5], off offset:128
	v_cvt_pk_bf16_f32 v4, v90, v91
	v_cvt_pk_bf16_f32 v5, v92, v93
	global_store_dwordx2 v[2:3], v[4:5], off offset:160
	v_cvt_pk_bf16_f32 v4, v74, v75
	v_cvt_pk_bf16_f32 v5, v76, v77
	global_store_dwordx2 v[2:3], v[4:5], off offset:192
	v_cvt_pk_bf16_f32 v4, v122, v123
	v_cvt_pk_bf16_f32 v5, v124, v125
	global_store_dwordx2 v[2:3], v[4:5], off offset:224
	v_add_co_u32_e32 v2, vcc, s62, v2
	v_cvt_pk_bf16_f32 v4, v114, v115
	v_cvt_pk_bf16_f32 v5, v116, v117
	v_addc_co_u32_e32 v3, vcc, 0, v3, vcc
	global_store_dwordx2 v[2:3], v[4:5], off
	v_cvt_pk_bf16_f32 v4, v106, v107
	v_cvt_pk_bf16_f32 v5, v108, v109
	global_store_dwordx2 v[2:3], v[4:5], off offset:32
	v_cvt_pk_bf16_f32 v4, v102, v103
	v_cvt_pk_bf16_f32 v5, v104, v105
	global_store_dwordx2 v[2:3], v[4:5], off offset:64
	v_cvt_pk_bf16_f32 v4, v86, v87
	v_cvt_pk_bf16_f32 v5, v88, v89
	global_store_dwordx2 v[2:3], v[4:5], off offset:96
	v_cvt_pk_bf16_f32 v4, v78, v79
	v_cvt_pk_bf16_f32 v5, v80, v81
	global_store_dwordx2 v[2:3], v[4:5], off offset:128
	v_cvt_pk_bf16_f32 v4, v98, v99
	v_cvt_pk_bf16_f32 v5, v100, v101
	global_store_dwordx2 v[2:3], v[4:5], off offset:160
	v_cvt_pk_bf16_f32 v4, v82, v83
	v_cvt_pk_bf16_f32 v5, v84, v85
	s_add_i32 s6, s65, 0xc0
	global_store_dwordx2 v[2:3], v[4:5], off offset:192
	v_cvt_pk_bf16_f32 v4, v134, v135
	v_cvt_pk_bf16_f32 v5, v136, v137
	s_cmpk_gt_i32 s65, 0x13f
	s_mov_b32 s65, s6
	global_store_dwordx2 v[2:3], v[4:5], off offset:224
	s_barrier
	s_cbranch_scc0 .LBB0_773
.LBB0_776:
	s_waitcnt vmcnt(0)
	s_mov_b64 s[6:7], 0
